# diff attention software-pipelined: K frags of tile t+1 prefetched early, its QK MFMAs interleaved with the row-max ops of tile t
# speedup vs baseline: 1.0090x; 1.0082x over previous
.LBB0_362:
	v_cmp_le_i32_e32 vcc, s94, v229
	s_and_saveexec_b64 s[12:13], vcc
	s_cbranch_execz .LBB0_372
	s_mov_b32 s99, 0x4800
	s_bitcmp1_b32 s26, 0
	s_cselect_b32 s99, 0x9000, s99
	v_add3_u32 v242, v232, v233, s99
	ds_read_b128 v[162:165], v242 offset:9216
	ds_read_b128 v[158:161], v242 offset:13824
	ds_read_b128 v[154:157], v242 offset:18432
	ds_read_b128 v[150:153], v242 offset:23040
	s_mov_b32 s101, 0
	s_cmp_ge_u32 s27, s22
	s_cbranch_scc1 .Lkr_skip1
	s_add_i32 s99, s94, 64
	v_cmp_le_i32_e32 vcc, s99, v229
	s_cbranch_vccz .Lkr_skip1
	s_mov_b32 s101, 1
	s_mov_b32 s99, 0x2400
	v_add3_u32 v148, v232, v238, s99
	ds_read_b128 v[114:117], v148
	ds_read_b128 v[118:121], v148 offset:4608
	ds_read_b128 v[122:125], v148 offset:32
	ds_read_b128 v[126:129], v148 offset:4640
	ds_read_b128 v[130:133], v148 offset:64
	ds_read_b128 v[134:137], v148 offset:4672
	ds_read_b128 v[138:141], v148 offset:96
	ds_read_b128 v[142:145], v148 offset:4704

.LBB0_365:
	s_andn2_saveexec_b64 s[0:1], s[0:1]
	s_cbranch_execz .LBB0_367
	v_fma_f32 v180, v82, s82, v176
	v_fma_f32 v181, v83, s82, v176
	v_fma_f32 v182, v84, s82, v176
	v_fma_f32 v183, v85, s82, v176
	v_fma_f32 v184, v86, s82, v176
	v_fma_f32 v185, v87, s82, v176
	v_fma_f32 v186, v88, s82, v176
	v_fma_f32 v187, v89, s82, v176
	v_fma_f32 v192, v90, s82, v176
	v_fma_f32 v193, v91, s82, v176
	v_fma_f32 v206, v92, s82, v176
	v_fma_f32 v207, v93, s82, v176
	v_fma_f32 v188, v94, s82, v176
	v_fma_f32 v189, v95, s82, v176
	v_fma_f32 v190, v96, s82, v176
	v_fma_f32 v191, v97, s82, v176
	v_fma_f32 v204, v66, s82, v176
	v_fma_f32 v205, v67, s82, v176
	v_fma_f32 v208, v68, s82, v176
	v_fma_f32 v209, v69, s82, v176
	v_fma_f32 v210, v70, s82, v176
	v_fma_f32 v211, v71, s82, v176
	v_fma_f32 v212, v72, s82, v176
	v_fma_f32 v213, v73, s82, v176
	v_fma_f32 v214, v74, s82, v176
	v_fma_f32 v215, v75, s82, v176
	v_fma_f32 v216, v76, s82, v176
	v_fma_f32 v217, v77, s82, v176
	v_fma_f32 v218, v78, s82, v176
	v_fma_f32 v219, v79, s82, v176
	v_fma_f32 v220, v80, s82, v176
	v_fma_f32 v221, v81, s82, v176
	s_cmp_eq_u32 s101, 0
	s_cbranch_scc1 .Lfar_plain1
	s_waitcnt lgkmcnt(7)
	v_mfma_f32_32x32x16_bf16 v[82:97], v[114:117], v[98:101], 0
	v_max_f32_e32 v0, v180, v181
	v_max_f32_e32 v146, v182, v183
	v_max3_f32 v0, v0, s33, v146
	s_waitcnt lgkmcnt(6)
	v_mfma_f32_32x32x16_bf16 v[66:81], v[118:121], v[98:101], 0
	v_max_f32_e32 v146, v184, v185
	v_max_f32_e32 v147, v186, v187
	v_max3_f32 v0, v0, v146, v147
	s_waitcnt lgkmcnt(5)
	v_mfma_f32_32x32x16_bf16 v[82:97], v[122:125], v[102:105], v[82:97]
	v_max_f32_e32 v146, v192, v193
	v_max_f32_e32 v147, v206, v207
	v_max3_f32 v0, v0, v146, v147
	s_waitcnt lgkmcnt(4)
	v_mfma_f32_32x32x16_bf16 v[66:81], v[126:129], v[102:105], v[66:81]
	v_max_f32_e32 v146, v188, v189
	v_max_f32_e32 v147, v190, v191
	v_max3_f32 v0, v0, v146, v147
	s_waitcnt lgkmcnt(3)
	v_mfma_f32_32x32x16_bf16 v[82:97], v[130:133], v[106:109], v[82:97]
	v_max_f32_e32 v148, v204, v205
	v_max_f32_e32 v149, v208, v209
	v_max3_f32 v0, v0, v148, v149
	s_waitcnt lgkmcnt(2)
	v_mfma_f32_32x32x16_bf16 v[66:81], v[134:137], v[106:109], v[66:81]
	v_max_f32_e32 v148, v210, v211
	v_max_f32_e32 v149, v212, v213
	v_max3_f32 v0, v0, v148, v149
	s_waitcnt lgkmcnt(1)
	v_mfma_f32_32x32x16_bf16 v[82:97], v[138:141], v[110:113], v[82:97]
	v_max_f32_e32 v148, v214, v215
	v_max_f32_e32 v149, v216, v217
	v_max3_f32 v0, v0, v148, v149
	s_waitcnt lgkmcnt(0)
	v_mfma_f32_32x32x16_bf16 v[66:81], v[142:145], v[110:113], v[66:81]
	v_max_f32_e32 v148, v218, v219
	v_max_f32_e32 v149, v220, v221
	v_max3_f32 v243, v0, v148, v149
	s_mov_b32 s101, 0
	s_branch .Lfar_done1
.Lfar_plain1:
	v_max_f32_e32 v0, v180, v181
	v_max_f32_e32 v146, v182, v183
	v_max3_f32 v0, v0, s33, v146
	v_max_f32_e32 v146, v184, v185
	v_max_f32_e32 v147, v186, v187
	v_max3_f32 v0, v0, v146, v147
	v_max_f32_e32 v146, v192, v193
	v_max_f32_e32 v147, v206, v207
	v_max3_f32 v0, v0, v146, v147
	v_max_f32_e32 v146, v188, v189
	v_max_f32_e32 v147, v190, v191
	v_max3_f32 v0, v0, v146, v147
	v_max_f32_e32 v148, v204, v205
	v_max_f32_e32 v149, v208, v209
	v_max3_f32 v0, v0, v148, v149
	v_max_f32_e32 v148, v210, v211
	v_max_f32_e32 v149, v212, v213
	v_max3_f32 v0, v0, v148, v149
	v_max_f32_e32 v148, v214, v215
	v_max_f32_e32 v149, v216, v217
	v_max3_f32 v0, v0, v148, v149
	v_max_f32_e32 v148, v218, v219
	v_max_f32_e32 v149, v220, v221
	v_max3_f32 v243, v0, v148, v149
.Lfar_done1:
.LBB0_367:
	s_or_b64 exec, exec, s[0:1]
	s_cmp_eq_u32 s26, 0
	s_cselect_b64 s[0:1], -1, 0
	s_and_b64 vcc, exec, s[0:1]
	s_mov_b64 s[14:15], s[0:1]
	s_cbranch_vccnz .LBB0_369
	v_cmp_lt_f32_e32 vcc, s92, v243
	s_cmp_lg_u64 vcc, 0
	s_cselect_b64 s[14:15], -1, 0

.LBB0_371:
	s_cmp_eq_u32 s101, 0
	s_cbranch_scc1 .Lqn_skip1
	s_waitcnt lgkmcnt(7)
	v_mfma_f32_32x32x16_bf16 v[82:97], v[114:117], v[98:101], 0
	s_waitcnt lgkmcnt(6)
	v_mfma_f32_32x32x16_bf16 v[66:81], v[118:121], v[98:101], 0
	s_waitcnt lgkmcnt(5)
	v_mfma_f32_32x32x16_bf16 v[82:97], v[122:125], v[102:105], v[82:97]
	s_waitcnt lgkmcnt(4)
	v_mfma_f32_32x32x16_bf16 v[66:81], v[126:129], v[102:105], v[66:81]
	s_waitcnt lgkmcnt(3)
	v_mfma_f32_32x32x16_bf16 v[82:97], v[130:133], v[106:109], v[82:97]
	s_waitcnt lgkmcnt(2)
	v_mfma_f32_32x32x16_bf16 v[66:81], v[134:137], v[106:109], v[66:81]
	s_waitcnt lgkmcnt(1)
	v_mfma_f32_32x32x16_bf16 v[82:97], v[138:141], v[110:113], v[82:97]
	s_waitcnt lgkmcnt(0)
	v_mfma_f32_32x32x16_bf16 v[66:81], v[142:145], v[110:113], v[66:81]

.LBB0_378:
	s_add_i32 s0, s94, 64
	v_cmp_le_i32_e32 vcc, s0, v229
	s_and_saveexec_b64 s[10:11], vcc
	s_cbranch_execz .LBB0_387
	s_mov_b32 s99, 0x4800
	s_bitcmp1_b32 s27, 0
	s_cselect_b32 s99, 0x9000, s99
	v_add3_u32 v242, v232, v233, s99
	ds_read_b128 v[162:165], v242 offset:9216
	ds_read_b128 v[158:161], v242 offset:13824
	ds_read_b128 v[154:157], v242 offset:18432
	ds_read_b128 v[150:153], v242 offset:23040
	s_mov_b32 s101, 0
	s_add_i32 s99, s26, 2
	s_cmp_ge_u32 s99, s22
	s_cbranch_scc1 .Lkr_skip2
	s_add_i32 s99, s94, 128
	v_cmp_le_i32_e32 vcc, s99, v229
	s_cbranch_vccz .Lkr_skip2
	s_mov_b32 s101, 1
	s_mov_b32 s99, 0x4800
	v_add3_u32 v148, v232, v238, s99
	ds_read_b128 v[114:117], v148
	ds_read_b128 v[118:121], v148 offset:4608
	ds_read_b128 v[122:125], v148 offset:32
	ds_read_b128 v[126:129], v148 offset:4640
	ds_read_b128 v[130:133], v148 offset:64
	ds_read_b128 v[134:137], v148 offset:4672
	ds_read_b128 v[138:141], v148 offset:96
	ds_read_b128 v[142:145], v148 offset:4704

.LBB0_384:
	v_fma_f32 v180, v82, s82, v176
	v_fma_f32 v181, v83, s82, v176
	v_fma_f32 v182, v84, s82, v176
	v_fma_f32 v183, v85, s82, v176
	v_fma_f32 v184, v86, s82, v176
	v_fma_f32 v185, v87, s82, v176
	v_fma_f32 v186, v88, s82, v176
	v_fma_f32 v187, v89, s82, v176
	v_fma_f32 v192, v90, s82, v176
	v_fma_f32 v193, v91, s82, v176
	v_fma_f32 v206, v92, s82, v176
	v_fma_f32 v207, v93, s82, v176
	v_fma_f32 v188, v94, s82, v176
	v_fma_f32 v189, v95, s82, v176
	v_fma_f32 v190, v96, s82, v176
	v_fma_f32 v191, v97, s82, v176
	v_fma_f32 v204, v66, s82, v176
	v_fma_f32 v205, v67, s82, v176
	v_fma_f32 v208, v68, s82, v176
	v_fma_f32 v209, v69, s82, v176
	v_fma_f32 v210, v70, s82, v176
	v_fma_f32 v211, v71, s82, v176
	v_fma_f32 v212, v72, s82, v176
	v_fma_f32 v213, v73, s82, v176
	v_fma_f32 v214, v74, s82, v176
	v_fma_f32 v215, v75, s82, v176
	v_fma_f32 v216, v76, s82, v176
	v_fma_f32 v217, v77, s82, v176
	v_fma_f32 v218, v78, s82, v176
	v_fma_f32 v219, v79, s82, v176
	v_fma_f32 v220, v80, s82, v176
	v_fma_f32 v221, v81, s82, v176
	s_cmp_eq_u32 s101, 0
	s_cbranch_scc1 .Lfar_plain2
	s_waitcnt lgkmcnt(7)
	v_mfma_f32_32x32x16_bf16 v[82:97], v[114:117], v[98:101], 0
	v_max_f32_e32 v0, v180, v181
	v_max_f32_e32 v146, v182, v183
	v_max3_f32 v0, v0, s33, v146
	s_waitcnt lgkmcnt(6)
	v_mfma_f32_32x32x16_bf16 v[66:81], v[118:121], v[98:101], 0
	v_max_f32_e32 v146, v184, v185
	v_max_f32_e32 v147, v186, v187
	v_max3_f32 v0, v0, v146, v147
	s_waitcnt lgkmcnt(5)
	v_mfma_f32_32x32x16_bf16 v[82:97], v[122:125], v[102:105], v[82:97]
	v_max_f32_e32 v146, v192, v193
	v_max_f32_e32 v147, v206, v207
	v_max3_f32 v0, v0, v146, v147
	s_waitcnt lgkmcnt(4)
	v_mfma_f32_32x32x16_bf16 v[66:81], v[126:129], v[102:105], v[66:81]
	v_max_f32_e32 v146, v188, v189
	v_max_f32_e32 v147, v190, v191
	v_max3_f32 v0, v0, v146, v147
	s_waitcnt lgkmcnt(3)
	v_mfma_f32_32x32x16_bf16 v[82:97], v[130:133], v[106:109], v[82:97]
	v_max_f32_e32 v148, v204, v205
	v_max_f32_e32 v149, v208, v209
	v_max3_f32 v0, v0, v148, v149
	s_waitcnt lgkmcnt(2)
	v_mfma_f32_32x32x16_bf16 v[66:81], v[134:137], v[106:109], v[66:81]
	v_max_f32_e32 v148, v210, v211
	v_max_f32_e32 v149, v212, v213
	v_max3_f32 v0, v0, v148, v149
	s_waitcnt lgkmcnt(1)
	v_mfma_f32_32x32x16_bf16 v[82:97], v[138:141], v[110:113], v[82:97]
	v_max_f32_e32 v148, v214, v215
	v_max_f32_e32 v149, v216, v217
	v_max3_f32 v0, v0, v148, v149
	s_waitcnt lgkmcnt(0)
	v_mfma_f32_32x32x16_bf16 v[66:81], v[142:145], v[110:113], v[66:81]
	v_max_f32_e32 v148, v218, v219
	v_max_f32_e32 v149, v220, v221
	v_max3_f32 v243, v0, v148, v149
	s_mov_b32 s101, 0
	s_branch .Lfar_done2

.Lfar_done2:
	s_or_b64 exec, exec, s[0:1]
	v_cmp_lt_f32_e32 vcc, s92, v243
	s_cbranch_vccnz .LBB0_382

.LBB0_391:
	s_add_i32 s0, s94, 0x80
	v_cmp_le_i32_e32 vcc, s0, v229
	s_and_saveexec_b64 s[10:11], vcc
	s_cbranch_execz .LBB0_400
	s_mov_b32 s99, 0x4800
	s_bitcmp1_b32 s26, 0
	s_cselect_b32 s99, 0x9000, s99
	v_add3_u32 v242, v232, v233, s99
	ds_read_b128 v[162:165], v242 offset:9216
	ds_read_b128 v[158:161], v242 offset:13824
	ds_read_b128 v[154:157], v242 offset:18432
	ds_read_b128 v[150:153], v242 offset:23040
	s_mov_b32 s101, 0
	s_cmp_ge_u32 s12, s22
	s_cbranch_scc1 .Lkr_skip3
	s_add_i32 s99, s94, 192
	v_cmp_le_i32_e32 vcc, s99, v229
	s_cbranch_vccz .Lkr_skip3
	s_mov_b32 s101, 1
	s_mov_b32 s99, 0x0
	v_add3_u32 v148, v232, v238, s99
	ds_read_b128 v[114:117], v148
	ds_read_b128 v[118:121], v148 offset:4608
	ds_read_b128 v[122:125], v148 offset:32
	ds_read_b128 v[126:129], v148 offset:4640
	ds_read_b128 v[130:133], v148 offset:64
	ds_read_b128 v[134:137], v148 offset:4672
	ds_read_b128 v[138:141], v148 offset:96
	ds_read_b128 v[142:145], v148 offset:4704
